# final RMSNorm rows remapped to the own bx%8 group so the last seam (step 13 -> final) is also a group-local barrier
# speedup vs baseline: 1.0117x; 1.0025x over previous
.LBB0_515:
	s_waitcnt vmcnt(0)
	s_waitcnt vmcnt(0) lgkmcnt(0)
	s_barrier
	s_and_saveexec_b64 s[0:1], s[62:63]
	s_cbranch_execz .LBB0_202
	v_readlane_b32 s6, v254, 49
	s_mov_b32 s9, 0x39f3
	s_nop 0
	s_lshr_b32 s12, s9, s6
	s_and_b32 s12, s12, s100
	s_and_b32 s12, s12, 1
	s_cmp_eq_u32 s12, 0
	s_cbranch_scc1 .Lgbar
	s_lshl_b32 s12, 2, s6
	s_sub_i32 s12, s12, 1
	s_and_b32 s12, s12, s9
	s_bcnt1_i32_b32 s12, s12
	s_lshl_b32 s9, s12, 5
	v_readlane_b32 s8, v252, 0
	v_readlane_b32 s10, v252, 45
	v_readlane_b32 s11, v252, 46
	s_and_b32 s8, s8, 7
	s_mov_b32 s16, 0x0e060301
	s_mov_b32 s17, 0xb058281c
	s_cmp_eq_u32 s6, 1
	s_cbranch_scc1 .Llb_tab
	s_mov_b32 s16, 0x0a060301
	s_mov_b32 s17, 0x88482414
	s_cmp_eq_u32 s6, 6
	s_cbranch_scc1 .Llb_tab
	s_mov_b32 s16, 0x0c060301
	s_mov_b32 s17, 0xa070381c
	s_cmp_eq_u32 s6, 8
	s_cbranch_scc1 .Llb_tab
	s_lshl_b32 s13, 1, s8
	s_branch .Llb_have

.LBB0_566:
	s_movk_i32 s101, 0x7fff
	s_cmp_eq_u32 s100, 1
	s_cbranch_scc0 .Lfin_nomap
	v_readlane_b32 s1, v252, 0
	s_nop 0
	s_and_b32 s2, s1, 7
	s_lshr_b32 s3, s1, 3
	s_lshl_b32 s4, s2, 12
	s_lshl_b32 s3, s3, 3
	s_add_i32 s3, s3, s4
	s_add_i32 s4, s4, 0xfff
	s_mov_b32 s101, s4
	s_movk_i32 s5, 0x100
	s_movk_i32 s6, 0x300
	s_mov_b32 s20, 32
	v_writelane_b32 v252, s3, 48
	v_writelane_b32 v252, s5, 51
	v_writelane_b32 v252, s6, 58
	s_nop 1

.LBB0_568:
	s_add_i32 s0, s0, s18
	s_cmp_gt_i32 s0, s101
	s_cbranch_scc1 .LBB0_575

	.amdhsa_kernel _Z14fwd_megakernel4Args
		.amdhsa_group_segment_fixed_size 0
		.amdhsa_private_segment_fixed_size 0
		.amdhsa_kernarg_size 416
		.amdhsa_user_sgpr_count 2
		.amdhsa_user_sgpr_dispatch_ptr 0
		.amdhsa_user_sgpr_queue_ptr 0
		.amdhsa_user_sgpr_kernarg_segment_ptr 1
		.amdhsa_user_sgpr_dispatch_id 0
		.amdhsa_user_sgpr_kernarg_preload_length 0
		.amdhsa_user_sgpr_kernarg_preload_offset 0
		.amdhsa_user_sgpr_private_segment_size 0
		.amdhsa_uses_dynamic_stack 0
		.amdhsa_enable_private_segment 0
		.amdhsa_system_sgpr_workgroup_id_x 1
		.amdhsa_system_sgpr_workgroup_id_y 0
		.amdhsa_system_sgpr_workgroup_id_z 0
		.amdhsa_system_sgpr_workgroup_info 0
		.amdhsa_system_vgpr_workitem_id 2
		.amdhsa_next_free_vgpr 256
		.amdhsa_next_free_sgpr 102
		.amdhsa_accum_offset 256
		.amdhsa_reserve_vcc 1
		.amdhsa_float_round_mode_32 0
		.amdhsa_float_round_mode_16_64 0
		.amdhsa_float_denorm_mode_32 3
		.amdhsa_float_denorm_mode_16_64 3
		.amdhsa_dx10_clamp 1
		.amdhsa_ieee_mode 1
		.amdhsa_fp16_overflow 0
		.amdhsa_tg_split 0
		.amdhsa_exception_fp_ieee_invalid_op 0
		.amdhsa_exception_fp_denorm_src 0
		.amdhsa_exception_fp_ieee_div_zero 0
		.amdhsa_exception_fp_ieee_overflow 0
		.amdhsa_exception_fp_ieee_underflow 0
		.amdhsa_exception_fp_ieee_inexact 0
		.amdhsa_exception_int_div_zero 0
	.end_amdhsa_kernel

amdhsa.kernels:
  - .agpr_count:     0
    .args:
      - .offset:         0
        .size:           160
        .value_kind:     by_value
      - .offset:         160
        .size:           4
        .value_kind:     hidden_block_count_x
      - .offset:         164
        .size:           4
        .value_kind:     hidden_block_count_y
      - .offset:         168
        .size:           4
        .value_kind:     hidden_block_count_z
      - .offset:         172
        .size:           2
        .value_kind:     hidden_group_size_x
      - .offset:         174
        .size:           2
        .value_kind:     hidden_group_size_y
      - .offset:         176
        .size:           2
        .value_kind:     hidden_group_size_z
      - .offset:         178
        .size:           2
        .value_kind:     hidden_remainder_x
      - .offset:         180
        .size:           2
        .value_kind:     hidden_remainder_y
      - .offset:         182
        .size:           2
        .value_kind:     hidden_remainder_z
      - .offset:         200
        .size:           8
        .value_kind:     hidden_global_offset_x
      - .offset:         208
        .size:           8
        .value_kind:     hidden_global_offset_y
      - .offset:         216
        .size:           8
        .value_kind:     hidden_global_offset_z
      - .offset:         224
        .size:           2
        .value_kind:     hidden_grid_dims
      - .offset:         248
        .size:           8
        .value_kind:     hidden_multigrid_sync_arg
      - .offset:         280
        .size:           4
        .value_kind:     hidden_dynamic_lds_size
    .group_segment_fixed_size: 0
    .kernarg_segment_align: 8
    .kernarg_segment_size: 416
    .language:       OpenCL C
    .language_version:
      - 2
      - 0
    .max_flat_workgroup_size: 512
    .name:           _Z14fwd_megakernel4Args
    .private_segment_fixed_size: 0
    .sgpr_count:     108
    .sgpr_spill_count: 202
    .symbol:         _Z14fwd_megakernel4Args.kd
    .uniform_work_group_size: 1
    .uses_dynamic_stack: false
    .vgpr_count:     256
    .vgpr_spill_count: 0
    .wavefront_size: 64
